# v41 + hyena context loops two trips per pass with two register sets (next trip's 10 LDS reads in flight under the current trip's multiply-adds)
# baseline (speedup 1.0000x reference)
; #define GAS __attribute__((address_space(1)))
; __device__ __forceinline__ void hyena_ctx(Frame& F, int l, int ch, LAS float* S, const LAS float* CT, bool wr = true) {
;     ...
;         float y = 0.f;
;         for (int mI = 0; mI < CTXL; ++mI) { const int d = n - mI; y += zb[b * 256 + mI] * (d >= 0 ? hfl[d] : hbl[CTXL + d]); }
;         y += CT[12 + o] * zb[b * 256 + n];
;         const GAS float* hx = o == 0 ? hx1 : hx2; const int xo = o == 0 ? 512 : 1024;
;         const int xp = o == 0 ? 1 : 2; const float r = conv3(hx + b * CTXL, n, CTXL, CT[3 * xp], CT[3 * xp + 1], CT[3 * xp + 2], CT[9 + xp]) * y;
.LBB0_997:
	s_or_b64 exec, exec, s[18:19]
	v_mov_b32_e32 v16, 0
	s_mov_b32 s5, 7
	v_mov_b32_e32 v8, v0
	v_mov_b32_e32 v9, v4
	v_mov_b32_e32 v10, v1
	v_mov_b32_e32 v13, 0x7ec
	v_mov_b32_e32 v17, 0xfec
	v_mov_b32_e32 v26, 0x7e8
	v_mov_b32_e32 v27, 0xfe8
	v_mov_b32_e32 v28, 0x7e4
	v_mov_b32_e32 v29, 0xfe4
	s_waitcnt lgkmcnt(0)
	s_barrier
	ds_read_b128 v[18:21], v10
	ds_read_b128 v[22:25], v10 offset:16
	v_add_u32_e32 v196, 0xfe4, v9
	ds_read_b32 v188, v196 offset:28
	ds_read_b32 v189, v196 offset:24
	ds_read_b32 v190, v196 offset:20
	ds_read_b32 v191, v196 offset:16
	ds_read_b32 v192, v196 offset:12
	ds_read_b32 v193, v196 offset:8
	ds_read_b32 v194, v196 offset:4
	ds_read_b32 v195, v196 offset:0
	v_add_u32_e32 v10, 32, v10
	v_subrev_u32_e32 v9, 32, v9
.LBB0_998:
	ds_read_b128 v[198:201], v10
	ds_read_b128 v[202:205], v10 offset:16
	v_add_u32_e32 v30, 0xfe4, v9
	ds_read_b32 v206, v30 offset:28
	ds_read_b32 v207, v30 offset:24
	ds_read_b32 v208, v30 offset:20
	ds_read_b32 v209, v30 offset:16
	ds_read_b32 v210, v30 offset:12
	ds_read_b32 v211, v30 offset:8
	ds_read_b32 v218, v30 offset:4
	ds_read_b32 v197, v30 offset:0
	v_add_u32_e32 v10, 32, v10
	v_subrev_u32_e32 v9, 32, v9
	s_waitcnt lgkmcnt(10)
	v_fmac_f32_e32 v16, v18, v188
	v_fmac_f32_e32 v16, v19, v189
	v_fmac_f32_e32 v16, v20, v190
	v_fmac_f32_e32 v16, v21, v191
	v_fmac_f32_e32 v16, v22, v192
	v_fmac_f32_e32 v16, v23, v193
	v_fmac_f32_e32 v16, v24, v194
	v_fmac_f32_e32 v16, v25, v195
	ds_read_b128 v[18:21], v10
	ds_read_b128 v[22:25], v10 offset:16
	v_add_u32_e32 v196, 0xfe4, v9
	ds_read_b32 v188, v196 offset:28
	ds_read_b32 v189, v196 offset:24
	ds_read_b32 v190, v196 offset:20
	ds_read_b32 v191, v196 offset:16
	ds_read_b32 v192, v196 offset:12
	ds_read_b32 v193, v196 offset:8
	ds_read_b32 v194, v196 offset:4
	ds_read_b32 v195, v196 offset:0
	v_add_u32_e32 v10, 32, v10
	v_subrev_u32_e32 v9, 32, v9
	v_add_u32_e32 v8, -16, v8
	s_add_i32 s5, s5, 16
	s_cmpk_eq_i32 s5, 0x107
	s_waitcnt lgkmcnt(10)
	v_fmac_f32_e32 v16, v198, v206
	v_fmac_f32_e32 v16, v199, v207
	v_fmac_f32_e32 v16, v200, v208
	v_fmac_f32_e32 v16, v201, v209
	v_fmac_f32_e32 v16, v202, v210
	v_fmac_f32_e32 v16, v203, v211
	v_fmac_f32_e32 v16, v204, v218
	v_fmac_f32_e32 v16, v205, v197
	s_cbranch_scc0 .LBB0_998
	s_waitcnt lgkmcnt(0)
	v_subrev_u32_e32 v10, 32, v10
	v_add_u32_e32 v9, 32, v9
	s_add_i32 s18, s12, 0x400
	s_mul_i32 s13, s18, 0x20800
	s_mul_hi_i32 s5, s18, 0x20800
	s_add_u32 s20, s0, s13
	s_addc_u32 s21, s2, s5
	v_lshl_add_u64 v[8:9], v[2:3], 2, s[20:21]
	v_lshl_add_u64 v[12:13], v[8:9], 0, v[176:177]
	v_add_co_u32_e32 v8, vcc, 0x20000, v12
	s_mov_b64 s[20:21], 0x20000
	s_nop 0
	v_addc_co_u32_e32 v9, vcc, 0, v13, vcc
	global_load_dword v18, v[8:9], off
	v_mov_b32_e32 v8, s4
	ds_read_b64 v[10:11], v8 offset:16
	ds_read2_b32 v[8:9], v8 offset0:10 offset1:12
	ds_read_b32 v17, v15
	v_mov_b32_e32 v29, 0xfe4
	v_mov_b32_e32 v28, 0x7e4
	v_mov_b32_e32 v27, 0xfe8
	v_mov_b32_e32 v26, 0x7e8
	v_mov_b32_e32 v19, 0xfec
	v_lshl_add_u64 v[12:13], v[12:13], 0, s[20:21]
	s_waitcnt vmcnt(0) lgkmcnt(1)
	v_fma_f32 v8, v10, v18, v8
	s_and_saveexec_b64 s[20:21], s[8:9]
	s_cbranch_execz .LBB0_1001
	global_load_dword v18, v[12:13], off offset:-4
	s_add_i32 s5, s3, 0x2680c
	v_mov_b32_e32 v10, s5
	ds_read_b32 v10, v10
	s_waitcnt vmcnt(0) lgkmcnt(0)
	v_fmac_f32_e32 v8, v10, v18

; #define GAS __attribute__((address_space(1)))
; __device__ __forceinline__ void hyena_ctx(Frame& F, int l, int ch, LAS float* S, const LAS float* CT, bool wr = true) {
;     ...
;         float y = 0.f;
;         for (int mI = 0; mI < CTXL; ++mI) { const int d = n - mI; y += zb[b * 256 + mI] * (d >= 0 ? hfl[d] : hbl[CTXL + d]); }
;         y += CT[12 + o] * zb[b * 256 + n];
;         const GAS float* hx = o == 0 ? hx1 : hx2; const int xo = o == 0 ? 512 : 1024;
;         const int xp = o == 0 ? 1 : 2; const float r = conv3(hx + b * CTXL, n, CTXL, CT[3 * xp], CT[3 * xp + 1], CT[3 * xp + 2], CT[9 + xp]) * y;
.LBB0_1007:
	s_or_b64 exec, exec, s[20:21]
	v_mov_b32_e32 v16, 0
	s_mov_b32 s5, 7
	v_mov_b32_e32 v8, v0
	v_mov_b32_e32 v9, v4
	v_mov_b32_e32 v10, v1
	v_mov_b32_e32 v13, 0x7ec
	v_mov_b32_e32 v17, v19
	s_waitcnt lgkmcnt(0)
	s_barrier
	ds_read_b128 v[18:21], v10
	ds_read_b128 v[22:25], v10 offset:16
	v_add_u32_e32 v196, 0xfe4, v9
	ds_read_b32 v188, v196 offset:28
	ds_read_b32 v189, v196 offset:24
	ds_read_b32 v190, v196 offset:20
	ds_read_b32 v191, v196 offset:16
	ds_read_b32 v192, v196 offset:12
	ds_read_b32 v193, v196 offset:8
	ds_read_b32 v194, v196 offset:4
	ds_read_b32 v195, v196 offset:0
	v_add_u32_e32 v10, 32, v10
	v_subrev_u32_e32 v9, 32, v9
.LBB0_1008:
	ds_read_b128 v[198:201], v10
	ds_read_b128 v[202:205], v10 offset:16
	v_add_u32_e32 v30, 0xfe4, v9
	ds_read_b32 v206, v30 offset:28
	ds_read_b32 v207, v30 offset:24
	ds_read_b32 v208, v30 offset:20
	ds_read_b32 v209, v30 offset:16
	ds_read_b32 v210, v30 offset:12
	ds_read_b32 v211, v30 offset:8
	ds_read_b32 v218, v30 offset:4
	ds_read_b32 v197, v30 offset:0
	v_add_u32_e32 v10, 32, v10
	v_subrev_u32_e32 v9, 32, v9
	s_waitcnt lgkmcnt(10)
	v_fmac_f32_e32 v16, v18, v188
	v_fmac_f32_e32 v16, v19, v189
	v_fmac_f32_e32 v16, v20, v190
	v_fmac_f32_e32 v16, v21, v191
	v_fmac_f32_e32 v16, v22, v192
	v_fmac_f32_e32 v16, v23, v193
	v_fmac_f32_e32 v16, v24, v194
	v_fmac_f32_e32 v16, v25, v195
	ds_read_b128 v[18:21], v10
	ds_read_b128 v[22:25], v10 offset:16
	v_add_u32_e32 v196, 0xfe4, v9
	ds_read_b32 v188, v196 offset:28
	ds_read_b32 v189, v196 offset:24
	ds_read_b32 v190, v196 offset:20
	ds_read_b32 v191, v196 offset:16
	ds_read_b32 v192, v196 offset:12
	ds_read_b32 v193, v196 offset:8
	ds_read_b32 v194, v196 offset:4
	ds_read_b32 v195, v196 offset:0
	v_add_u32_e32 v10, 32, v10
	v_subrev_u32_e32 v9, 32, v9
	v_add_u32_e32 v8, -16, v8
	s_add_i32 s5, s5, 16
	s_cmpk_lg_i32 s5, 0x107
	s_waitcnt lgkmcnt(10)
	v_fmac_f32_e32 v16, v198, v206
	v_fmac_f32_e32 v16, v199, v207
	v_fmac_f32_e32 v16, v200, v208
	v_fmac_f32_e32 v16, v201, v209
	v_fmac_f32_e32 v16, v202, v210
	v_fmac_f32_e32 v16, v203, v211
	v_fmac_f32_e32 v16, v204, v218
	v_fmac_f32_e32 v16, v205, v197
	s_cbranch_scc1 .LBB0_1008
	s_waitcnt lgkmcnt(0)
	v_subrev_u32_e32 v10, 32, v10
	v_add_u32_e32 v9, 32, v9
	v_mov_b32_e32 v10, s4
	s_add_i32 s4, s12, 0x600
	s_mul_hi_i32 s5, s4, 0x20800
	s_mul_i32 s4, s4, 0x20800
	s_add_u32 s4, s0, s4
	s_addc_u32 s5, s2, s5
	v_lshl_add_u64 v[12:13], v[2:3], 2, s[4:5]
	v_lshl_add_u64 v[18:19], v[12:13], 0, v[176:177]
	s_mov_b64 s[4:5], 0x20000
	v_lshl_add_u64 v[12:13], v[18:19], 0, s[4:5]
	v_add_co_u32_e32 v18, vcc, 0x20000, v18
	ds_read2_b32 v[8:9], v10 offset0:11 offset1:13
	ds_read_b32 v17, v15
	v_addc_co_u32_e32 v19, vcc, 0, v19, vcc
	global_load_dword v18, v[18:19], off
	ds_read2_b32 v[10:11], v10 offset0:7 offset1:8
	s_waitcnt vmcnt(0) lgkmcnt(0)
	v_fma_f32 v8, v10, v18, v8
	s_and_saveexec_b64 s[18:19], s[8:9]
	s_cbranch_execz .LBB0_1011
	global_load_dword v18, v[12:13], off offset:-4
	s_add_i32 s3, s3, 0x26818
	v_mov_b32_e32 v10, s3
	ds_read_b32 v10, v10
	s_waitcnt vmcnt(0) lgkmcnt(0)
	v_fmac_f32_e32 v8, v10, v18
